# P2: column-tile index permuted after decode so the expensive sigmoid-epilogue tiles are spread over all workgroups instead of the odd XCDs only
# speedup vs baseline: 1.0130x; 1.0008x over previous
;     __device__ __forceinline__ bool next(int i, Unit& u) const { return decode(i * G + c, u); }
; #define PG8_STAGE(bufoff, gbase, voff) do { _Pragma("unroll") for (int _i = 0; _i < 2; ++_i) \
;         __builtin_amdgcn_global_load_lds((const unsigned*)((const char*)(gbase) + (voff)[_i]), (LAS unsigned*)(lds + (bufoff) + ldsw + _i * 8192), 16, 0, 0); } while (0)
;     __device__ __forceinline__ bool decode(int L, Unit& u) const {
;     ...
;         int wgid = L; { const int q = nwg / NXCD, r = nwg % NXCD, xcd = wgid % NXCD, off = wgid / NXCD; wgid = (xcd < r ? xcd * (q + 1) : r * (q + 1) + (xcd - r) * q) + off; }
;         const int nig = WGM * nN, gid = wgid / nig, fm = gid * WGM, gsz = (nMt - fm) < WGM ? (nMt - fm) : WGM;
;         const int pmt = fm + ((wgid % nig) % gsz); u.pn = (wgid % nig) / gsz; u.bz = pmt / nMb; u.pm = pmt % nMb; return true;
; template <class Epi, class Sched, bool DEFER>
; __device__ __forceinline__ void gemm_fast_core(LAS unsigned char* lds, const GemmP g, const Sched& S, const Epi& E, f32x4 (&acc)[2][2][4][2], Unit& cur) {
;     ...
;     for (int i = 0; i < 2; ++i) { int R, C; stage_rc(tid * 16 + i * 8192, R, C); voffA[i] = (unsigned)(R * g.lda + C) * 2u; voffB[i] = (unsigned)(R * g.ldb + C) * 2u; }
;     const size_t kstep = (size_t)(BK * 2);
;     const size_t hstepA = (size_t)HALF * g.lda * 2, hstepB = (size_t)HALF * g.ldb * 2;
;     const unsigned ldsw = (unsigned)wid * 1024u;
;     const int aoff = lds_byte(wr * 64 + fr, fq * 8), boff = lds_byte(wc * 32 + fr, fq * 8);
;     ...
;     Unit nxt; int ui = 0;
;     if (!S.next(0, cur)) return;
; #pragma unroll
;     for (int a = 0; a < 2; ++a)
; #pragma unroll
;         for (int b = 0; b < 2; ++b)
; #pragma unroll
;             for (int m = 0; m < 4; ++m)
; #pragma unroll
;                 for (int n = 0; n < 2; ++n) acc[a][b][m][n] = (f32x4){0.f, 0.f, 0.f, 0.f};
;     bf16x8 At[4][2], B0[2][2], B1[2][2];
;     const char* cA = (const char*)g.aptr(cur); const char* cB = (const char*)g.bptr(cur);
;     PG8_STAGE(PG8_SB(0, 0), cB, voffB); PG8_STAGE(PG8_SB(0, 1), cB + hstepB, voffB); PG8_STAGE(PG8_SA(0, 0), cA, voffA); PG8_STAGE(PG8_SA(0, 1), cA + hstepA, voffA);
;     if (wr == 1) PG8_BAR;
;     PG8_WAIT_V(2); PG8_BAR;
;     PG8_STAGE(PG8_SB(1, 0), cB + kstep, voffB); PG8_STAGE(PG8_SA(1, 0), cA + kstep, voffA); PG8_STAGE(PG8_SB(1, 1), cB + hstepB + kstep, voffB);
.LBB0_222:
	s_and_b64 vcc, exec, s[16:17]
	s_cbranch_vccz .LBB0_224
	s_ashr_i32 s2, s88, 31
	s_lshr_b32 s2, s2, 29
	s_add_i32 s2, s88, s2
	s_ashr_i32 s3, s2, 3
	s_and_b32 s2, s2, -8
	s_sub_i32 s2, s88, s2
	s_cmp_lt_i32 s2, 0
	s_movk_i32 s4, 0x85
	s_cselect_b32 s4, s4, 0x84
	s_mul_i32 s2, s2, s4
	s_add_i32 s2, s2, s3
	s_mul_hi_i32 s3, s2, 0x3e0f83e1
	s_lshr_b32 s4, s3, 31
	s_ashr_i32 s3, s3, 6
	s_add_i32 s3, s3, s4
	s_lshl_b32 s4, s3, 3
	s_mulk_i32 s3, 0x108
	s_sub_i32 s2, s2, s3
	s_sext_i32_i16 s3, s2
	s_bfe_u32 s3, s3, 0x3001c
	s_add_i32 s3, s2, s3
	s_sext_i32_i16 s5, s3
	s_and_b32 s3, s3, 0xfff8
	s_sub_i32 s2, s2, s3
	s_sext_i32_i16 s2, s2
	s_add_i32 s2, s4, s2
	s_ashr_i32 s3, s2, 31
	s_lshr_b32 s3, s3, 27
	s_add_i32 s3, s2, s3
	s_andn2_b32 s3, s3, 31
	s_ashr_i32 s26, s5, 3
	s_sub_i32 s2, s2, s3
	s_cmp_gt_u32 s26, 31
	s_cbranch_scc1 .Lp2sig_a
	s_bfe_u32 s3, s26, 0x10002
	s_lshl_b32 s3, s3, 4
	s_xor_b32 s3, s3, s26
	s_and_b32 s3, s3, 16
	s_xor_b32 s26, s26, s3
	s_lshr_b32 s3, s3, 2
	s_xor_b32 s26, s26, s3
.Lp2sig_a:
	s_mov_b64 s[4:5], -1
.LBB0_224:
	v_writelane_b32 v254, s72, 44
	s_andn2_b64 vcc, exec, s[4:5]
	s_nop 0
	v_writelane_b32 v254, s73, 45
	s_cbranch_vccnz .LBB0_947
	v_ashrrev_i32_e32 v1, 31, v8
	v_lshrrev_b32_e32 v1, 26, v1
	v_add_u32_e32 v1, v8, v1
	v_ashrrev_i32_e32 v9, 6, v1
	v_bfe_i32 v1, v8, 27, 1
	v_lshlrev_b32_e32 v0, 4, v8
	v_lshrrev_b32_e32 v1, 22, v1
	v_add_u32_e32 v1, v0, v1
	v_and_b32_e32 v1, 0xfffffc00, v1
	v_sub_u32_e32 v1, v0, v1
	v_lshrrev_b32_e32 v2, 4, v1
	v_bitop3_b32 v1, v2, v1, 32 bitop3:0x6c
	v_ashrrev_i32_e32 v3, 31, v1
	v_lshrrev_b32_e32 v3, 26, v3
	v_add_u32_e32 v3, v1, v3
	v_ashrrev_i32_e32 v10, 6, v3
	v_and_b32_e32 v3, 0xc0, v3
	v_sub_u32_e32 v1, v1, v3
	v_mov_b32_e32 v3, 1
	v_lshlrev_b32_e32 v2, 3, v9
	v_lshlrev_b32_e32 v4, 5, v9
	v_ashrrev_i16_sdwa v1, v3, sext(v1) dst_sel:DWORD dst_unused:UNUSED_PAD src0_sel:DWORD src1_sel:BYTE_0
	v_and_b32_e32 v2, 0xffff0, v2
	v_and_b32_e32 v4, 32, v4
	v_bfe_i32 v11, v1, 0, 16
	v_add_u32_e32 v1, v4, v11
	v_add_lshl_u32 v2, v10, v2, 12
	v_add_u32_e32 v0, 0x2000, v0
	v_lshl_add_u32 v128, v1, 1, v2
	v_ashrrev_i32_e32 v1, 31, v0
	v_lshrrev_b32_e32 v1, 22, v1
	v_add_u32_e32 v1, v0, v1
	v_ashrrev_i32_e32 v12, 10, v1
	v_mul_i32_i24_e32 v1, 0x400, v12
	v_sub_u32_e32 v0, v0, v1
	v_lshrrev_b32_e32 v1, 4, v0
	v_bitop3_b32 v0, v1, v0, 32 bitop3:0x6c
	v_ashrrev_i32_e32 v2, 31, v0
	v_lshrrev_b32_e32 v2, 26, v2
	v_add_u32_e32 v2, v0, v2
	s_ashr_i32 s16, s18, 6
	s_ashr_i32 s3, s2, 31
	s_ashr_i32 s27, s26, 31
	s_ashr_i32 s19, s18, 8
	v_ashrrev_i32_e32 v13, 6, v2
	v_and_b32_e32 v2, 0xc0, v2
	s_lshl_b32 s21, s16, 10
	s_lshl_b64 s[4:5], s[2:3], 20
	s_lshl_b64 s[22:23], s[26:27], 20
	v_sub_u32_e32 v0, v0, v2
	s_add_u32 s38, s10, s22
	v_lshlrev_b32_e32 v1, 3, v12
	v_lshlrev_b32_e32 v4, 5, v12
	v_ashrrev_i16_sdwa v0, v3, sext(v0) dst_sel:DWORD dst_unused:UNUSED_PAD src0_sel:DWORD src1_sel:BYTE_0
	s_addc_u32 s39, s11, s23
	s_add_i32 s48, s21, 0
	v_and_b32_e32 v1, 0xffff0, v1
	v_and_b32_e32 v4, 32, v4
	v_bfe_i32 v14, v0, 0, 16
	s_add_i32 m0, s48, 0x10000
	v_add_u32_e32 v0, v4, v14
	v_add_lshl_u32 v1, v13, v1, 12
	global_load_lds_dwordx4 v128, s[38:39]
	s_add_i32 m0, s48, 0x12000
	v_lshl_add_u32 v130, v0, 1, v1
	s_add_u32 s22, s38, 0x80000
	global_load_lds_dwordx4 v130, s[38:39]
	s_addc_u32 s23, s39, 0
	s_add_i32 m0, s48, 0x14000
	v_mov_b32_e32 v129, 0
	global_load_lds_dwordx4 v128, s[22:23]
	s_add_i32 m0, s48, 0x16000
	s_add_u32 s36, s90, s4
	s_addc_u32 s37, s91, s5
	s_add_i32 s49, s48, 0x2000
	global_load_lds_dwordx4 v130, s[22:23]
	s_mov_b32 m0, s48
	s_add_u32 s4, s36, 0x80000
	global_load_lds_dwordx4 v128, s[36:37]
	s_mov_b32 m0, s49
	s_addc_u32 s5, s37, 0
	s_add_i32 s68, s48, 0x4000
	global_load_lds_dwordx4 v130, s[36:37]
	s_mov_b32 m0, s68
	s_add_i32 s69, s48, 0x6000
	global_load_lds_dwordx4 v128, s[4:5]
	s_mov_b32 m0, s69
	v_mov_b32_e32 v131, v129
	global_load_lds_dwordx4 v130, s[4:5]
	s_cmp_eq_u32 s19, 1
	s_mov_b32 s73, 0
	v_lshl_add_u64 v[6:7], s[38:39], 0, v[128:129]
	v_lshl_add_u64 v[4:5], s[38:39], 0, v[130:131]
	v_lshl_add_u64 v[0:1], s[36:37], 0, v[128:129]
	s_cselect_b64 s[4:5], -1, 0
	s_cmp_lg_u32 s19, 1
	v_lshl_add_u64 v[2:3], s[36:37], 0, v[130:131]
	s_cbranch_scc1 .LBB0_227
	s_barrier

;     __device__ __forceinline__ bool decode(int L, Unit& u) const {
;     ...
;         int wgid = L; { const int q = nwg / NXCD, r = nwg % NXCD, xcd = wgid % NXCD, off = wgid / NXCD; wgid = (xcd < r ? xcd * (q + 1) : r * (q + 1) + (xcd - r) * q) + off; }
;         const int nig = WGM * nN, gid = wgid / nig, fm = gid * WGM, gsz = (nMt - fm) < WGM ? (nMt - fm) : WGM;
;         const int pmt = fm + ((wgid % nig) % gsz); u.pn = (wgid % nig) / gsz; u.bz = pmt / nMb; u.pm = pmt % nMb; return true;
.LBB0_233:
	s_andn2_b64 vcc, exec, s[30:31]
	s_cbranch_vccnz .LBB0_235
	s_ashr_i32 s22, s3, 31
	s_lshr_b32 s22, s22, 29
	s_add_i32 s22, s3, s22
	s_ashr_i32 s23, s22, 3
	s_and_b32 s22, s22, -8
	s_sub_i32 s3, s3, s22
	s_cmp_lt_i32 s3, 0
	s_movk_i32 s22, 0x85
	s_cselect_b32 s22, s22, 0x84
	s_mul_i32 s3, s3, s22
	s_add_i32 s3, s3, s23
	s_mul_hi_i32 s22, s3, 0x3e0f83e1
	s_lshr_b32 s23, s22, 31
	s_ashr_i32 s22, s22, 6
	s_add_i32 s22, s22, s23
	s_lshl_b32 s23, s22, 3
	s_mulk_i32 s22, 0x108
	s_sub_i32 s3, s3, s22
	s_bfe_u32 s22, s3, 0x3001c
	s_add_i32 s22, s3, s22
	s_sext_i32_i16 s24, s22
	s_and_b32 s22, s22, 0xfff8
	s_sub_i32 s3, s3, s22
	s_sext_i32_i16 s3, s3
	s_add_i32 s3, s23, s3
	s_ashr_i32 s23, s3, 31
	s_lshr_b32 s23, s23, 27
	s_add_i32 s23, s3, s23
	s_andn2_b32 s23, s23, 31
	s_ashr_i32 s22, s24, 3
	s_sub_i32 s24, s3, s23
	s_cmp_gt_u32 s22, 31
	s_cbranch_scc1 .Lp2sig_b
	s_bfe_u32 s23, s22, 0x10002
	s_lshl_b32 s23, s23, 4
	s_xor_b32 s23, s23, s22
	s_and_b32 s23, s23, 16
	s_xor_b32 s22, s22, s23
	s_lshr_b32 s23, s23, 2
	s_xor_b32 s22, s22, s23
.Lp2sig_b:
	s_mov_b64 s[28:29], -1
